# G1: per-head softmax blocks rewritten: compact item write, one transposed wave reduction for the 8 softmax sums, dense 2-items-per-lane finalize (division, scale loads, table-half partition)
# baseline (speedup 1.0000x reference)
.LBB0_994:
	s_or_b64 exec, exec, s[16:17]
	v_ashrrev_i32_e32 v5, 31, v2
	v_or_b32_e32 v5, 0x80000000, v5
	v_bitop3_b32 v5, v5, s48, v2 bitop3:0x48
	v_bitop3_b32 v39, v5, 63, v124 bitop3:0x36
	ds_write_b32 v133, v39 offset:2816
	s_waitcnt lgkmcnt(0)
	s_and_b64 s[14:15], exec, vcc
	s_or_b64 s[34:35], s[14:15], s[34:35]
	v_mov_b32_e32 v40, v29
	v_mov_b32_e32 v41, v30
	v_mov_b32_e32 v42, v31
	v_mov_b32_e32 v43, v33
	v_mov_b32_e32 v44, v34
	v_mov_b32_e32 v45, v36
	v_mov_b32_e32 v46, v37
	v_mov_b32_e32 v47, v39
	v_mov_b32_e32 v48, 0
	v_mov_b32_e32 v49, 0
	v_mov_b32_e32 v50, 0
	v_mov_b32_e32 v51, 0
	v_mov_b32_e32 v52, 0
	v_mov_b32_e32 v53, 0
	v_mov_b32_e32 v54, 0
	v_mov_b32_e32 v55, 0
	v_mov_b32_dpp v48, v40 quad_perm:[1,0,3,2] row_mask:0xf bank_mask:0xf
	v_mov_b32_dpp v49, v41 quad_perm:[1,0,3,2] row_mask:0xf bank_mask:0xf
	v_mov_b32_dpp v50, v42 quad_perm:[1,0,3,2] row_mask:0xf bank_mask:0xf
	v_mov_b32_dpp v51, v43 quad_perm:[1,0,3,2] row_mask:0xf bank_mask:0xf
	v_mov_b32_dpp v52, v44 quad_perm:[1,0,3,2] row_mask:0xf bank_mask:0xf
	v_mov_b32_dpp v53, v45 quad_perm:[1,0,3,2] row_mask:0xf bank_mask:0xf
	v_mov_b32_dpp v54, v46 quad_perm:[1,0,3,2] row_mask:0xf bank_mask:0xf
	v_mov_b32_dpp v55, v47 quad_perm:[1,0,3,2] row_mask:0xf bank_mask:0xf
	v_med3_u32 v40, v40, v48, v196
	v_med3_u32 v41, v41, v49, v196
	v_med3_u32 v42, v42, v50, v196
	v_med3_u32 v43, v43, v51, v196
	v_med3_u32 v44, v44, v52, v196
	v_med3_u32 v45, v45, v53, v196
	v_med3_u32 v46, v46, v54, v196
	v_med3_u32 v47, v47, v55, v196
	v_mov_b32_dpp v48, v40 quad_perm:[3,2,1,0] row_mask:0xf bank_mask:0xf
	v_mov_b32_dpp v49, v41 quad_perm:[3,2,1,0] row_mask:0xf bank_mask:0xf
	v_mov_b32_dpp v50, v42 quad_perm:[3,2,1,0] row_mask:0xf bank_mask:0xf
	v_mov_b32_dpp v51, v43 quad_perm:[3,2,1,0] row_mask:0xf bank_mask:0xf
	v_mov_b32_dpp v52, v44 quad_perm:[3,2,1,0] row_mask:0xf bank_mask:0xf
	v_mov_b32_dpp v53, v45 quad_perm:[3,2,1,0] row_mask:0xf bank_mask:0xf
	v_mov_b32_dpp v54, v46 quad_perm:[3,2,1,0] row_mask:0xf bank_mask:0xf
	v_mov_b32_dpp v55, v47 quad_perm:[3,2,1,0] row_mask:0xf bank_mask:0xf
	v_med3_u32 v40, v40, v48, v197
	v_med3_u32 v41, v41, v49, v197
	v_med3_u32 v42, v42, v50, v197
	v_med3_u32 v43, v43, v51, v197
	v_med3_u32 v44, v44, v52, v197
	v_med3_u32 v45, v45, v53, v197
	v_med3_u32 v46, v46, v54, v197
	v_med3_u32 v47, v47, v55, v197
	v_mov_b32_dpp v48, v40 quad_perm:[1,0,3,2] row_mask:0xf bank_mask:0xf
	v_mov_b32_dpp v49, v41 quad_perm:[1,0,3,2] row_mask:0xf bank_mask:0xf
	v_mov_b32_dpp v50, v42 quad_perm:[1,0,3,2] row_mask:0xf bank_mask:0xf
	v_mov_b32_dpp v51, v43 quad_perm:[1,0,3,2] row_mask:0xf bank_mask:0xf
	v_mov_b32_dpp v52, v44 quad_perm:[1,0,3,2] row_mask:0xf bank_mask:0xf
	v_mov_b32_dpp v53, v45 quad_perm:[1,0,3,2] row_mask:0xf bank_mask:0xf
	v_mov_b32_dpp v54, v46 quad_perm:[1,0,3,2] row_mask:0xf bank_mask:0xf
	v_mov_b32_dpp v55, v47 quad_perm:[1,0,3,2] row_mask:0xf bank_mask:0xf
	v_med3_u32 v40, v40, v48, v196
	v_med3_u32 v41, v41, v49, v196
	v_med3_u32 v42, v42, v50, v196
	v_med3_u32 v43, v43, v51, v196
	v_med3_u32 v44, v44, v52, v196
	v_med3_u32 v45, v45, v53, v196
	v_med3_u32 v46, v46, v54, v196
	v_med3_u32 v47, v47, v55, v196
	v_mov_b32_dpp v48, v40 row_half_mirror row_mask:0xf bank_mask:0xf
	v_mov_b32_dpp v49, v41 row_half_mirror row_mask:0xf bank_mask:0xf
	v_mov_b32_dpp v50, v42 row_half_mirror row_mask:0xf bank_mask:0xf
	v_mov_b32_dpp v51, v43 row_half_mirror row_mask:0xf bank_mask:0xf
	v_mov_b32_dpp v52, v44 row_half_mirror row_mask:0xf bank_mask:0xf
	v_mov_b32_dpp v53, v45 row_half_mirror row_mask:0xf bank_mask:0xf
	v_mov_b32_dpp v54, v46 row_half_mirror row_mask:0xf bank_mask:0xf
	v_mov_b32_dpp v55, v47 row_half_mirror row_mask:0xf bank_mask:0xf
	v_med3_u32 v40, v40, v48, v198
	v_med3_u32 v41, v41, v49, v198
	v_med3_u32 v42, v42, v50, v198
	v_med3_u32 v43, v43, v51, v198
	v_med3_u32 v44, v44, v52, v198
	v_med3_u32 v45, v45, v53, v198
	v_med3_u32 v46, v46, v54, v198
	v_med3_u32 v47, v47, v55, v198
	v_mov_b32_dpp v48, v40 quad_perm:[2,3,0,1] row_mask:0xf bank_mask:0xf
	v_mov_b32_dpp v49, v41 quad_perm:[2,3,0,1] row_mask:0xf bank_mask:0xf
	v_mov_b32_dpp v50, v42 quad_perm:[2,3,0,1] row_mask:0xf bank_mask:0xf
	v_mov_b32_dpp v51, v43 quad_perm:[2,3,0,1] row_mask:0xf bank_mask:0xf
	v_mov_b32_dpp v52, v44 quad_perm:[2,3,0,1] row_mask:0xf bank_mask:0xf
	v_mov_b32_dpp v53, v45 quad_perm:[2,3,0,1] row_mask:0xf bank_mask:0xf
	v_mov_b32_dpp v54, v46 quad_perm:[2,3,0,1] row_mask:0xf bank_mask:0xf
	v_mov_b32_dpp v55, v47 quad_perm:[2,3,0,1] row_mask:0xf bank_mask:0xf
	v_med3_u32 v40, v40, v48, v197
	v_med3_u32 v41, v41, v49, v197
	v_med3_u32 v42, v42, v50, v197
	v_med3_u32 v43, v43, v51, v197
	v_med3_u32 v44, v44, v52, v197
	v_med3_u32 v45, v45, v53, v197
	v_med3_u32 v46, v46, v54, v197
	v_med3_u32 v47, v47, v55, v197
	v_mov_b32_dpp v48, v40 quad_perm:[1,0,3,2] row_mask:0xf bank_mask:0xf
	v_mov_b32_dpp v49, v41 quad_perm:[1,0,3,2] row_mask:0xf bank_mask:0xf
	v_mov_b32_dpp v50, v42 quad_perm:[1,0,3,2] row_mask:0xf bank_mask:0xf
	v_mov_b32_dpp v51, v43 quad_perm:[1,0,3,2] row_mask:0xf bank_mask:0xf
	v_mov_b32_dpp v52, v44 quad_perm:[1,0,3,2] row_mask:0xf bank_mask:0xf
	v_mov_b32_dpp v53, v45 quad_perm:[1,0,3,2] row_mask:0xf bank_mask:0xf
	v_mov_b32_dpp v54, v46 quad_perm:[1,0,3,2] row_mask:0xf bank_mask:0xf
	v_mov_b32_dpp v55, v47 quad_perm:[1,0,3,2] row_mask:0xf bank_mask:0xf
	v_med3_u32 v40, v40, v48, v196
	v_med3_u32 v41, v41, v49, v196
	v_med3_u32 v42, v42, v50, v196
	v_med3_u32 v43, v43, v51, v196
	v_med3_u32 v44, v44, v52, v196
	v_med3_u32 v45, v45, v53, v196
	v_med3_u32 v46, v46, v54, v196
	v_med3_u32 v47, v47, v55, v196
	v_mov_b32_dpp v48, v40 row_mirror row_mask:0xf bank_mask:0xf
	v_mov_b32_dpp v49, v41 row_mirror row_mask:0xf bank_mask:0xf
	v_mov_b32_dpp v50, v42 row_mirror row_mask:0xf bank_mask:0xf
	v_mov_b32_dpp v51, v43 row_mirror row_mask:0xf bank_mask:0xf
	v_mov_b32_dpp v52, v44 row_mirror row_mask:0xf bank_mask:0xf
	v_mov_b32_dpp v53, v45 row_mirror row_mask:0xf bank_mask:0xf
	v_mov_b32_dpp v54, v46 row_mirror row_mask:0xf bank_mask:0xf
	v_mov_b32_dpp v55, v47 row_mirror row_mask:0xf bank_mask:0xf
	v_med3_u32 v40, v40, v48, v199
	v_med3_u32 v41, v41, v49, v199
	v_med3_u32 v42, v42, v50, v199
	v_med3_u32 v43, v43, v51, v199
	v_med3_u32 v44, v44, v52, v199
	v_med3_u32 v45, v45, v53, v199
	v_med3_u32 v46, v46, v54, v199
	v_med3_u32 v47, v47, v55, v199
	v_mov_b32_dpp v48, v40 row_shl:4 row_mask:0xf bank_mask:0x5
	v_mov_b32_dpp v49, v41 row_shl:4 row_mask:0xf bank_mask:0x5
	v_mov_b32_dpp v50, v42 row_shl:4 row_mask:0xf bank_mask:0x5
	v_mov_b32_dpp v51, v43 row_shl:4 row_mask:0xf bank_mask:0x5
	v_mov_b32_dpp v52, v44 row_shl:4 row_mask:0xf bank_mask:0x5
	v_mov_b32_dpp v53, v45 row_shl:4 row_mask:0xf bank_mask:0x5
	v_mov_b32_dpp v54, v46 row_shl:4 row_mask:0xf bank_mask:0x5
	v_mov_b32_dpp v55, v47 row_shl:4 row_mask:0xf bank_mask:0x5
	v_mov_b32_dpp v48, v40 row_shr:4 row_mask:0xf bank_mask:0xa
	v_mov_b32_dpp v49, v41 row_shr:4 row_mask:0xf bank_mask:0xa
	v_mov_b32_dpp v50, v42 row_shr:4 row_mask:0xf bank_mask:0xa
	v_mov_b32_dpp v51, v43 row_shr:4 row_mask:0xf bank_mask:0xa
	v_mov_b32_dpp v52, v44 row_shr:4 row_mask:0xf bank_mask:0xa
	v_mov_b32_dpp v53, v45 row_shr:4 row_mask:0xf bank_mask:0xa
	v_mov_b32_dpp v54, v46 row_shr:4 row_mask:0xf bank_mask:0xa
	v_mov_b32_dpp v55, v47 row_shr:4 row_mask:0xf bank_mask:0xa
	v_med3_u32 v40, v40, v48, v198
	v_med3_u32 v41, v41, v49, v198
	v_med3_u32 v42, v42, v50, v198
	v_med3_u32 v43, v43, v51, v198
	v_med3_u32 v44, v44, v52, v198
	v_med3_u32 v45, v45, v53, v198
	v_med3_u32 v46, v46, v54, v198
	v_med3_u32 v47, v47, v55, v198
	v_mov_b32_dpp v48, v40 quad_perm:[2,3,0,1] row_mask:0xf bank_mask:0xf
	v_mov_b32_dpp v49, v41 quad_perm:[2,3,0,1] row_mask:0xf bank_mask:0xf
	v_mov_b32_dpp v50, v42 quad_perm:[2,3,0,1] row_mask:0xf bank_mask:0xf
	v_mov_b32_dpp v51, v43 quad_perm:[2,3,0,1] row_mask:0xf bank_mask:0xf
	v_mov_b32_dpp v52, v44 quad_perm:[2,3,0,1] row_mask:0xf bank_mask:0xf
	v_mov_b32_dpp v53, v45 quad_perm:[2,3,0,1] row_mask:0xf bank_mask:0xf
	v_mov_b32_dpp v54, v46 quad_perm:[2,3,0,1] row_mask:0xf bank_mask:0xf
	v_mov_b32_dpp v55, v47 quad_perm:[2,3,0,1] row_mask:0xf bank_mask:0xf
	v_med3_u32 v40, v40, v48, v197
	v_med3_u32 v41, v41, v49, v197
	v_med3_u32 v42, v42, v50, v197
	v_med3_u32 v43, v43, v51, v197
	v_med3_u32 v44, v44, v52, v197
	v_med3_u32 v45, v45, v53, v197
	v_med3_u32 v46, v46, v54, v197
	v_med3_u32 v47, v47, v55, v197
	v_mov_b32_dpp v48, v40 quad_perm:[1,0,3,2] row_mask:0xf bank_mask:0xf
	v_mov_b32_dpp v49, v41 quad_perm:[1,0,3,2] row_mask:0xf bank_mask:0xf
	v_mov_b32_dpp v50, v42 quad_perm:[1,0,3,2] row_mask:0xf bank_mask:0xf
	v_mov_b32_dpp v51, v43 quad_perm:[1,0,3,2] row_mask:0xf bank_mask:0xf
	v_mov_b32_dpp v52, v44 quad_perm:[1,0,3,2] row_mask:0xf bank_mask:0xf
	v_mov_b32_dpp v53, v45 quad_perm:[1,0,3,2] row_mask:0xf bank_mask:0xf
	v_mov_b32_dpp v54, v46 quad_perm:[1,0,3,2] row_mask:0xf bank_mask:0xf
	v_mov_b32_dpp v55, v47 quad_perm:[1,0,3,2] row_mask:0xf bank_mask:0xf
	v_med3_u32 v40, v40, v48, v196
	v_med3_u32 v41, v41, v49, v196
	v_med3_u32 v42, v42, v50, v196
	v_med3_u32 v43, v43, v51, v196
	v_med3_u32 v44, v44, v52, v196
	v_med3_u32 v45, v45, v53, v196
	v_med3_u32 v46, v46, v54, v196
	v_med3_u32 v47, v47, v55, v196
	v_mov_b32_e32 v56, v40
	v_mov_b32_e32 v57, v41
	v_mov_b32_e32 v58, v42
	v_mov_b32_e32 v59, v43
	v_mov_b32_e32 v60, v44
	v_mov_b32_e32 v61, v45
	v_mov_b32_e32 v62, v46
	v_mov_b32_e32 v63, v47
	v_permlane16_swap_b32_e32 v40, v56
	v_permlane16_swap_b32_e32 v41, v57
	v_permlane16_swap_b32_e32 v42, v58
	v_permlane16_swap_b32_e32 v43, v59
	v_permlane16_swap_b32_e32 v44, v60
	v_permlane16_swap_b32_e32 v45, v61
	v_permlane16_swap_b32_e32 v46, v62
	v_permlane16_swap_b32_e32 v47, v63
	v_max_u32_e32 v40, v40, v56
	v_max_u32_e32 v41, v41, v57
	v_max_u32_e32 v42, v42, v58
	v_max_u32_e32 v43, v43, v59
	v_max_u32_e32 v44, v44, v60
	v_max_u32_e32 v45, v45, v61
	v_max_u32_e32 v46, v46, v62
	v_max_u32_e32 v47, v47, v63
	v_mov_b32_dpp v48, v40 row_ror:8 row_mask:0xf bank_mask:0xf
	v_mov_b32_dpp v49, v41 row_ror:8 row_mask:0xf bank_mask:0xf
	v_mov_b32_dpp v50, v42 row_ror:8 row_mask:0xf bank_mask:0xf
	v_mov_b32_dpp v51, v43 row_ror:8 row_mask:0xf bank_mask:0xf
	v_mov_b32_dpp v52, v44 row_ror:8 row_mask:0xf bank_mask:0xf
	v_mov_b32_dpp v53, v45 row_ror:8 row_mask:0xf bank_mask:0xf
	v_mov_b32_dpp v54, v46 row_ror:8 row_mask:0xf bank_mask:0xf
	v_mov_b32_dpp v55, v47 row_ror:8 row_mask:0xf bank_mask:0xf
	v_med3_u32 v40, v40, v48, v203
	v_med3_u32 v41, v41, v49, v203
	v_med3_u32 v42, v42, v50, v203
	v_med3_u32 v43, v43, v51, v203
	v_med3_u32 v44, v44, v52, v203
	v_med3_u32 v45, v45, v53, v203
	v_med3_u32 v46, v46, v54, v203
	v_med3_u32 v47, v47, v55, v203
	v_mov_b32_dpp v48, v40 row_shl:4 row_mask:0xf bank_mask:0x5
	v_mov_b32_dpp v49, v41 row_shl:4 row_mask:0xf bank_mask:0x5
	v_mov_b32_dpp v50, v42 row_shl:4 row_mask:0xf bank_mask:0x5
	v_mov_b32_dpp v51, v43 row_shl:4 row_mask:0xf bank_mask:0x5
	v_mov_b32_dpp v52, v44 row_shl:4 row_mask:0xf bank_mask:0x5
	v_mov_b32_dpp v53, v45 row_shl:4 row_mask:0xf bank_mask:0x5
	v_mov_b32_dpp v54, v46 row_shl:4 row_mask:0xf bank_mask:0x5
	v_mov_b32_dpp v55, v47 row_shl:4 row_mask:0xf bank_mask:0x5
	v_mov_b32_dpp v48, v40 row_shr:4 row_mask:0xf bank_mask:0xa
	v_mov_b32_dpp v49, v41 row_shr:4 row_mask:0xf bank_mask:0xa
	v_mov_b32_dpp v50, v42 row_shr:4 row_mask:0xf bank_mask:0xa
	v_mov_b32_dpp v51, v43 row_shr:4 row_mask:0xf bank_mask:0xa
	v_mov_b32_dpp v52, v44 row_shr:4 row_mask:0xf bank_mask:0xa
	v_mov_b32_dpp v53, v45 row_shr:4 row_mask:0xf bank_mask:0xa
	v_mov_b32_dpp v54, v46 row_shr:4 row_mask:0xf bank_mask:0xa
	v_mov_b32_dpp v55, v47 row_shr:4 row_mask:0xf bank_mask:0xa
	v_med3_u32 v40, v40, v48, v202
	v_med3_u32 v41, v41, v49, v202
	v_med3_u32 v42, v42, v50, v202
	v_med3_u32 v43, v43, v51, v202
	v_med3_u32 v44, v44, v52, v202
	v_med3_u32 v45, v45, v53, v202
	v_med3_u32 v46, v46, v54, v202
	v_med3_u32 v47, v47, v55, v202
	v_mov_b32_dpp v48, v40 quad_perm:[2,3,0,1] row_mask:0xf bank_mask:0xf
	v_mov_b32_dpp v49, v41 quad_perm:[2,3,0,1] row_mask:0xf bank_mask:0xf
	v_mov_b32_dpp v50, v42 quad_perm:[2,3,0,1] row_mask:0xf bank_mask:0xf
	v_mov_b32_dpp v51, v43 quad_perm:[2,3,0,1] row_mask:0xf bank_mask:0xf
	v_mov_b32_dpp v52, v44 quad_perm:[2,3,0,1] row_mask:0xf bank_mask:0xf
	v_mov_b32_dpp v53, v45 quad_perm:[2,3,0,1] row_mask:0xf bank_mask:0xf
	v_mov_b32_dpp v54, v46 quad_perm:[2,3,0,1] row_mask:0xf bank_mask:0xf
	v_mov_b32_dpp v55, v47 quad_perm:[2,3,0,1] row_mask:0xf bank_mask:0xf
	v_med3_u32 v40, v40, v48, v201
	v_med3_u32 v41, v41, v49, v201
	v_med3_u32 v42, v42, v50, v201
	v_med3_u32 v43, v43, v51, v201
	v_med3_u32 v44, v44, v52, v201
	v_med3_u32 v45, v45, v53, v201
	v_med3_u32 v46, v46, v54, v201
	v_med3_u32 v47, v47, v55, v201
	v_mov_b32_dpp v48, v40 quad_perm:[1,0,3,2] row_mask:0xf bank_mask:0xf
	v_mov_b32_dpp v49, v41 quad_perm:[1,0,3,2] row_mask:0xf bank_mask:0xf
	v_mov_b32_dpp v50, v42 quad_perm:[1,0,3,2] row_mask:0xf bank_mask:0xf
	v_mov_b32_dpp v51, v43 quad_perm:[1,0,3,2] row_mask:0xf bank_mask:0xf
	v_mov_b32_dpp v52, v44 quad_perm:[1,0,3,2] row_mask:0xf bank_mask:0xf
	v_mov_b32_dpp v53, v45 quad_perm:[1,0,3,2] row_mask:0xf bank_mask:0xf
	v_mov_b32_dpp v54, v46 quad_perm:[1,0,3,2] row_mask:0xf bank_mask:0xf
	v_mov_b32_dpp v55, v47 quad_perm:[1,0,3,2] row_mask:0xf bank_mask:0xf
	v_med3_u32 v40, v40, v48, v200
	v_med3_u32 v41, v41, v49, v200
	v_med3_u32 v42, v42, v50, v200
	v_med3_u32 v43, v43, v51, v200
	v_med3_u32 v44, v44, v52, v200
	v_med3_u32 v45, v45, v53, v200
	v_med3_u32 v46, v46, v54, v200
	v_med3_u32 v47, v47, v55, v200
	v_mov_b32_e32 v56, v40
	v_mov_b32_e32 v57, v41
	v_mov_b32_e32 v58, v42
	v_mov_b32_e32 v59, v43
	v_mov_b32_e32 v60, v44
	v_mov_b32_e32 v61, v45
	v_mov_b32_e32 v62, v46
	v_mov_b32_e32 v63, v47
	v_permlane32_swap_b32_e32 v40, v56
	v_permlane32_swap_b32_e32 v41, v57
	v_permlane32_swap_b32_e32 v42, v58
	v_permlane32_swap_b32_e32 v43, v59
	v_permlane32_swap_b32_e32 v44, v60
	v_permlane32_swap_b32_e32 v45, v61
	v_permlane32_swap_b32_e32 v46, v62
	v_permlane32_swap_b32_e32 v47, v63
	v_max_u32_e32 v40, v40, v56
	v_max_u32_e32 v41, v41, v57
	v_max_u32_e32 v42, v42, v58
	v_max_u32_e32 v43, v43, v59
	v_max_u32_e32 v44, v44, v60
	v_max_u32_e32 v45, v45, v61
	v_max_u32_e32 v46, v46, v62
	v_max_u32_e32 v47, v47, v63
	v_min_u32_dpp v40, v40, v40 quad_perm:[1,0,3,2] row_mask:0xf bank_mask:0xf
	v_min_u32_dpp v41, v41, v41 quad_perm:[1,0,3,2] row_mask:0xf bank_mask:0xf
	v_min_u32_dpp v42, v42, v42 quad_perm:[1,0,3,2] row_mask:0xf bank_mask:0xf
	v_min_u32_dpp v43, v43, v43 quad_perm:[1,0,3,2] row_mask:0xf bank_mask:0xf
	v_min_u32_dpp v44, v44, v44 quad_perm:[1,0,3,2] row_mask:0xf bank_mask:0xf
	v_min_u32_dpp v45, v45, v45 quad_perm:[1,0,3,2] row_mask:0xf bank_mask:0xf
	v_min_u32_dpp v46, v46, v46 quad_perm:[1,0,3,2] row_mask:0xf bank_mask:0xf
	v_min_u32_dpp v47, v47, v47 quad_perm:[1,0,3,2] row_mask:0xf bank_mask:0xf
	v_min_u32_dpp v40, v40, v40 quad_perm:[2,3,0,1] row_mask:0xf bank_mask:0xf
	v_min_u32_dpp v41, v41, v41 quad_perm:[2,3,0,1] row_mask:0xf bank_mask:0xf
	v_min_u32_dpp v42, v42, v42 quad_perm:[2,3,0,1] row_mask:0xf bank_mask:0xf
	v_min_u32_dpp v43, v43, v43 quad_perm:[2,3,0,1] row_mask:0xf bank_mask:0xf
	v_min_u32_dpp v44, v44, v44 quad_perm:[2,3,0,1] row_mask:0xf bank_mask:0xf
	v_min_u32_dpp v45, v45, v45 quad_perm:[2,3,0,1] row_mask:0xf bank_mask:0xf
	v_min_u32_dpp v46, v46, v46 quad_perm:[2,3,0,1] row_mask:0xf bank_mask:0xf
	v_min_u32_dpp v47, v47, v47 quad_perm:[2,3,0,1] row_mask:0xf bank_mask:0xf
	v_min_u32_dpp v40, v40, v40 row_half_mirror row_mask:0xf bank_mask:0xf
	v_min_u32_dpp v41, v41, v41 row_half_mirror row_mask:0xf bank_mask:0xf
	v_min_u32_dpp v42, v42, v42 row_half_mirror row_mask:0xf bank_mask:0xf
	v_min_u32_dpp v43, v43, v43 row_half_mirror row_mask:0xf bank_mask:0xf
	v_min_u32_dpp v44, v44, v44 row_half_mirror row_mask:0xf bank_mask:0xf
	v_min_u32_dpp v45, v45, v45 row_half_mirror row_mask:0xf bank_mask:0xf
	v_min_u32_dpp v46, v46, v46 row_half_mirror row_mask:0xf bank_mask:0xf
	v_min_u32_dpp v47, v47, v47 row_half_mirror row_mask:0xf bank_mask:0xf
	v_min_u32_dpp v40, v40, v40 row_mirror row_mask:0xf bank_mask:0xf
	v_min_u32_dpp v41, v41, v41 row_mirror row_mask:0xf bank_mask:0xf
	v_min_u32_dpp v42, v42, v42 row_mirror row_mask:0xf bank_mask:0xf
	v_min_u32_dpp v43, v43, v43 row_mirror row_mask:0xf bank_mask:0xf
	v_min_u32_dpp v44, v44, v44 row_mirror row_mask:0xf bank_mask:0xf
	v_min_u32_dpp v45, v45, v45 row_mirror row_mask:0xf bank_mask:0xf
	v_min_u32_dpp v46, v46, v46 row_mirror row_mask:0xf bank_mask:0xf
	v_min_u32_dpp v47, v47, v47 row_mirror row_mask:0xf bank_mask:0xf
	v_readlane_b32 s80, v40, 0
	v_readlane_b32 s81, v41, 0
	v_readlane_b32 s82, v42, 0
	v_readlane_b32 s83, v43, 0
	v_readlane_b32 s84, v44, 0
	v_readlane_b32 s85, v45, 0
	v_readlane_b32 s86, v46, 0
	v_readlane_b32 s87, v47, 0
	v_cmp_gt_u32_e64 s[66:67], s80, v29
	v_cmp_gt_u32_e64 s[68:69], s81, v30
	v_cmp_gt_u32_e64 s[72:73], s82, v31
	v_cmp_gt_u32_e64 s[74:75], s83, v33
	v_cmp_gt_u32_e64 s[76:77], s84, v34
	v_cmp_gt_u32_e64 s[78:79], s85, v36
	v_cmp_gt_u32_e64 s[88:89], s86, v37
	v_cmp_gt_u32_e64 s[90:91], s87, v39
	s_andn2_b64 s[14:15], s[4:5], s[66:67]
	s_andn2_b64 s[16:17], s[4:5], s[68:69]
	s_andn2_b64 s[18:19], s[4:5], s[72:73]
	s_andn2_b64 s[20:21], s[4:5], s[74:75]
	s_andn2_b64 s[22:23], s[4:5], s[76:77]
	s_andn2_b64 s[24:25], s[4:5], s[78:79]
	s_andn2_b64 s[26:27], s[4:5], s[88:89]
	s_andn2_b64 s[28:29], s[4:5], s[90:91]
	s_movk_i32 s69, 0x7f
	v_readfirstlane_b32 s44, v27
	v_mbcnt_lo_u32_b32 v48, s14, 0
	v_mbcnt_hi_u32_b32 v48, s15, v48
	v_lshlrev_b32_e32 v25, 7, v25
	v_subrev_f32_e32 v27, s44, v27
	v_and_b32_e32 v26, 0x7f, v26
	v_mul_f32_e32 v27, 0x3fb8aa3b, v27
	v_and_or_b32 v25, v25, s49, v26
	v_exp_f32_e32 v27, v27
	v_lshl_add_u32 v56, v48, 2, v127
	s_nop 0
	v_cndmask_b32_e64 v40, 0, v27, s[14:15]
	s_and_saveexec_b64 s[42:43], s[14:15]
	ds_write_b32 v56, v25 offset:3072
	ds_write_b32 v56, v27 offset:3584
	s_mov_b64 exec, s[42:43]
	v_readfirstlane_b32 s44, v23
	v_mbcnt_lo_u32_b32 v49, s16, 0
	v_mbcnt_hi_u32_b32 v49, s17, v49
	v_lshlrev_b32_e32 v20, 7, v20
	v_subrev_f32_e32 v23, s44, v23
	v_and_b32_e32 v21, 0x7f, v21
	v_mul_f32_e32 v23, 0x3fb8aa3b, v23
	v_and_or_b32 v20, v20, s49, v21
	v_exp_f32_e32 v23, v23
	v_lshl_add_u32 v57, v49, 2, v127
	v_or_b32_e32 v20, 0x800000, v20
	v_cndmask_b32_e64 v41, 0, v23, s[16:17]
	s_and_saveexec_b64 s[42:43], s[16:17]
	ds_write_b32 v57, v20 offset:3136
	ds_write_b32 v57, v23 offset:3648
	s_mov_b64 exec, s[42:43]
	v_readfirstlane_b32 s44, v22
	v_mbcnt_lo_u32_b32 v50, s18, 0
	v_mbcnt_hi_u32_b32 v50, s19, v50
	v_lshlrev_b32_e32 v17, 7, v17
	v_subrev_f32_e32 v22, s44, v22
	v_and_b32_e32 v18, 0x7f, v18
	v_mul_f32_e32 v22, 0x3fb8aa3b, v22
	v_and_or_b32 v17, v17, s49, v18
	v_exp_f32_e32 v22, v22
	v_lshl_add_u32 v58, v50, 2, v127
	v_or_b32_e32 v17, 0x400000, v17
	v_cndmask_b32_e64 v42, 0, v22, s[18:19]
	s_and_saveexec_b64 s[42:43], s[18:19]
	ds_write_b32 v58, v17 offset:3200
	ds_write_b32 v58, v22 offset:3712
	s_mov_b64 exec, s[42:43]
	v_readfirstlane_b32 s44, v16
	v_mbcnt_lo_u32_b32 v51, s20, 0
	v_mbcnt_hi_u32_b32 v51, s21, v51
	v_lshlrev_b32_e32 v13, 7, v13
	v_subrev_f32_e32 v16, s44, v16
	v_and_b32_e32 v14, 0x7f, v14
	v_mul_f32_e32 v16, 0x3fb8aa3b, v16
	v_and_or_b32 v13, v13, s49, v14
	v_exp_f32_e32 v16, v16
	v_lshl_add_u32 v59, v51, 2, v127
	v_or_b32_e32 v13, 0xc00000, v13
	v_cndmask_b32_e64 v43, 0, v16, s[20:21]
	s_and_saveexec_b64 s[42:43], s[20:21]
	ds_write_b32 v59, v13 offset:3264
	ds_write_b32 v59, v16 offset:3776
	s_mov_b64 exec, s[42:43]
	v_readfirstlane_b32 s44, v15
	v_mbcnt_lo_u32_b32 v52, s22, 0
	v_mbcnt_hi_u32_b32 v52, s23, v52
	v_lshlrev_b32_e32 v10, 7, v10
	v_subrev_f32_e32 v15, s44, v15
	v_and_b32_e32 v11, 0x7f, v11
	v_mul_f32_e32 v15, 0x3fb8aa3b, v15
	v_and_or_b32 v10, v10, s49, v11
	v_exp_f32_e32 v15, v15
	v_lshl_add_u32 v60, v52, 2, v127
	v_or_b32_e32 v10, 0x200000, v10
	v_cndmask_b32_e64 v44, 0, v15, s[22:23]
	s_and_saveexec_b64 s[42:43], s[22:23]
	ds_write_b32 v60, v10 offset:3328
	ds_write_b32 v60, v15 offset:3840
	s_mov_b64 exec, s[42:43]
	v_readfirstlane_b32 s44, v9
	v_mbcnt_lo_u32_b32 v53, s24, 0
	v_mbcnt_hi_u32_b32 v53, s25, v53
	v_lshlrev_b32_e32 v6, 7, v6
	v_subrev_f32_e32 v9, s44, v9
	v_and_b32_e32 v7, 0x7f, v7
	v_mul_f32_e32 v9, 0x3fb8aa3b, v9
	v_and_or_b32 v6, v6, s49, v7
	v_exp_f32_e32 v9, v9
	v_lshl_add_u32 v61, v53, 2, v127
	v_or_b32_e32 v6, 0xa00000, v6
	v_cndmask_b32_e64 v45, 0, v9, s[24:25]
	s_and_saveexec_b64 s[42:43], s[24:25]
	ds_write_b32 v61, v6 offset:3392
	ds_write_b32 v61, v9 offset:3904
	s_mov_b64 exec, s[42:43]
	v_readfirstlane_b32 s44, v8
	v_mbcnt_lo_u32_b32 v54, s26, 0
	v_mbcnt_hi_u32_b32 v54, s27, v54
	v_lshlrev_b32_e32 v3, 7, v3
	v_subrev_f32_e32 v8, s44, v8
	v_and_b32_e32 v4, 0x7f, v4
	v_mul_f32_e32 v8, 0x3fb8aa3b, v8
	v_and_or_b32 v3, v3, s49, v4
	v_exp_f32_e32 v8, v8
	v_lshl_add_u32 v62, v54, 2, v127
	v_or_b32_e32 v3, 0x600000, v3
	v_cndmask_b32_e64 v46, 0, v8, s[26:27]
	s_and_saveexec_b64 s[42:43], s[26:27]
	ds_write_b32 v62, v3 offset:3456
	ds_write_b32 v62, v8 offset:3968
	s_mov_b64 exec, s[42:43]
	v_readfirstlane_b32 s44, v2
	v_mbcnt_lo_u32_b32 v55, s28, 0
	v_mbcnt_hi_u32_b32 v55, s29, v55
	v_lshlrev_b32_e32 v0, 7, v0
	v_subrev_f32_e32 v2, s44, v2
	v_and_b32_e32 v1, 0x7f, v1
	v_mul_f32_e32 v2, 0x3fb8aa3b, v2
	v_and_or_b32 v0, v0, s49, v1
	v_exp_f32_e32 v2, v2
	v_lshl_add_u32 v63, v55, 2, v127
	v_or_b32_e32 v0, 0xe00000, v0
	v_cndmask_b32_e64 v47, 0, v2, s[28:29]
	s_and_saveexec_b64 s[42:43], s[28:29]
	ds_write_b32 v63, v0 offset:3520
	ds_write_b32 v63, v2 offset:4032
	s_mov_b64 exec, s[42:43]
	s_nop 1
	v_permlane32_swap_b32_e32 v40, v41
	v_permlane32_swap_b32_e32 v42, v43
	v_permlane32_swap_b32_e32 v44, v45
	v_permlane32_swap_b32_e32 v46, v47
	v_add_f32_e32 v40, v40, v41
	v_add_f32_e32 v42, v42, v43
	v_add_f32_e32 v44, v44, v45
	v_add_f32_e32 v46, v46, v47
	s_nop 1
	v_permlane16_swap_b32_e32 v40, v42
	v_permlane16_swap_b32_e32 v44, v46
	v_add_f32_e32 v40, v40, v42
	v_add_f32_e32 v44, v44, v46
	s_nop 1
	v_add_f32_dpp v36, v40, v40 row_ror:8 row_mask:0xf bank_mask:0xf
	v_add_f32_dpp v36, v44, v44 row_ror:8 row_mask:0xf bank_mask:0xc
	s_nop 1
	v_add_f32_dpp v37, v36, v36 row_shl:4 row_mask:0xf bank_mask:0x5
	v_add_f32_dpp v37, v36, v36 row_shr:4 row_mask:0xf bank_mask:0xa
	s_nop 1
	v_add_f32_dpp v37, v37, v37 quad_perm:[2,3,0,1] row_mask:0xf bank_mask:0xf
	s_nop 1
	v_add_f32_dpp v37, v37, v37 quad_perm:[1,0,3,2] row_mask:0xf bank_mask:0xf
	v_lshl_add_u32 v16, v130, 2, v127
	ds_read2st64_b32 v[28:29], v16 offset0:12 offset1:14
	ds_read2st64_b32 v[30:31], v16 offset0:13 offset1:15
	v_sub_u32_e32 v12, s69, v130
	v_sub_u32_e32 v13, 63, v130
	s_waitcnt lgkmcnt(1)
	v_lshrrev_b32_e32 v32, 16, v28
	v_and_b32_e32 v38, 0xffff, v28
	s_waitcnt lgkmcnt(0)
	v_lshrrev_b32_e32 v33, 16, v30
	v_and_b32_e32 v39, 0xffff, v30
	ds_bpermute_b32 v34, v32, v37
	ds_bpermute_b32 v35, v33, v37
	v_lshlrev_b32_e32 v8, 2, v38
	v_lshlrev_b32_e32 v9, 2, v39
	global_load_dword v144, v8, s[36:37]
	global_load_dword v145, v8, s[38:39]
	global_load_dword v146, v9, s[36:37]
	global_load_dword v147, v9, s[38:39]
	v_lshrrev_b32_e32 v10, 7, v38
	v_lshrrev_b32_e32 v11, 7, v39
	v_xor_b32_e32 v10, v10, v38
	v_xor_b32_e32 v11, v11, v39
	v_and_b32_e32 v10, 64, v10
	v_and_b32_e32 v11, 64, v11
	v_cmp_eq_u32_e64 s[64:65], 0, v10
	v_cmp_eq_u32_e64 s[66:67], 0, v11
	s_nop 1
	v_mbcnt_lo_u32_b32 v14, s64, 0
	v_mbcnt_hi_u32_b32 v14, s65, v14
	v_mbcnt_lo_u32_b32 v15, s66, 0
	v_mbcnt_hi_u32_b32 v15, s67, v15
	s_bcnt1_i32_b64 s68, s[64:65]
	v_cndmask_b32_e64 v12, v12, 0, s[64:65]
	v_cndmask_b32_e64 v13, v13, 0, s[66:67]
	v_add_u32_e32 v12, v14, v12
	v_add3_u32 v13, v15, v13, s68
	v_lshl_add_u32 v142, v12, 2, v127
	v_lshl_add_u32 v143, v13, 2, v127
	s_waitcnt lgkmcnt(1)
	v_div_scale_f32 v0, s[72:73], v34, v34, v29
	v_rcp_f32_e32 v1, v0
	s_nop 0
	v_fma_f32 v2, -v0, v1, 1.0
	v_fmac_f32_e32 v1, v2, v1
	v_div_scale_f32 v2, vcc, v29, v34, v29
	v_mul_f32_e32 v3, v2, v1
	v_fma_f32 v4, -v0, v3, v2
	v_fmac_f32_e32 v3, v4, v1
	v_fma_f32 v0, -v0, v3, v2
	v_div_fmas_f32 v0, v0, v1, v3
	v_div_fixup_f32 v6, v0, v34, v29
	s_waitcnt lgkmcnt(0)
	v_div_scale_f32 v17, s[72:73], v35, v35, v31
	v_rcp_f32_e32 v18, v17
	s_nop 0
	v_fma_f32 v19, -v17, v18, 1.0
	v_fmac_f32_e32 v18, v19, v18
	v_div_scale_f32 v19, vcc, v31, v35, v31
	v_mul_f32_e32 v20, v19, v18
	v_fma_f32 v21, -v17, v20, v19
	v_fmac_f32_e32 v20, v21, v18
	v_fma_f32 v17, -v17, v20, v19
	v_div_fmas_f32 v17, v17, v18, v20
	v_div_fixup_f32 v7, v17, v35, v31
	ds_write2st64_b32 v142, v38, v6 offset0:12 offset1:14
	ds_write2st64_b32 v143, v39, v7 offset0:12 offset1:14
	v_ashrrev_i32_e32 v117, 31, v116
	v_lshlrev_b64 v[0:1], 11, v[116:117]
	s_waitcnt lgkmcnt(0)
	v_lshl_add_u64 v[0:1], v[120:121], 0, v[0:1]
	global_load_dwordx2 v[2:3], v[0:1], off
	global_load_dwordx2 v[4:5], v[0:1], off offset:256
	global_load_dwordx2 v[6:7], v[0:1], off offset:512
	global_load_dwordx2 v[8:9], v[0:1], off offset:768
	global_load_dwordx2 v[10:11], v[0:1], off offset:1024
	global_load_dwordx2 v[12:13], v[0:1], off offset:1280
	global_load_dwordx2 v[14:15], v[0:1], off offset:1536
	s_nop 0
	global_load_dwordx2 v[0:1], v[0:1], off offset:1792
	s_movk_i32 s63, 0xffe0
	v_mov_b32_e32 v183, v134
	s_waitcnt vmcnt(7)
	v_lshlrev_b32_e32 v16, 16, v2
	v_and_b32_e32 v2, 0xffff0000, v2
	v_lshlrev_b32_e32 v17, 16, v3
	v_and_b32_e32 v3, 0xffff0000, v3
	s_waitcnt vmcnt(6)
	v_lshlrev_b32_e32 v18, 16, v4
	v_and_b32_e32 v4, 0xffff0000, v4
	v_lshlrev_b32_e32 v19, 16, v5
	v_and_b32_e32 v5, 0xffff0000, v5
	s_waitcnt vmcnt(5)
	v_lshlrev_b32_e32 v20, 16, v6
	v_and_b32_e32 v6, 0xffff0000, v6
	v_lshlrev_b32_e32 v21, 16, v7
	v_and_b32_e32 v7, 0xffff0000, v7
	s_waitcnt vmcnt(4)
	v_lshlrev_b32_e32 v22, 16, v8
	v_and_b32_e32 v8, 0xffff0000, v8
	v_lshlrev_b32_e32 v23, 16, v9
	v_and_b32_e32 v9, 0xffff0000, v9
	s_waitcnt vmcnt(3)
	v_lshlrev_b32_e32 v24, 16, v10
	v_and_b32_e32 v10, 0xffff0000, v10
	v_lshlrev_b32_e32 v25, 16, v11
	v_and_b32_e32 v11, 0xffff0000, v11
	s_waitcnt vmcnt(2)
	v_lshlrev_b32_e32 v26, 16, v12
	v_and_b32_e32 v12, 0xffff0000, v12
	v_lshlrev_b32_e32 v27, 16, v13
	v_and_b32_e32 v13, 0xffff0000, v13
	s_waitcnt vmcnt(1)
	v_lshlrev_b32_e32 v28, 16, v14
	v_and_b32_e32 v14, 0xffff0000, v14
	v_lshlrev_b32_e32 v29, 16, v15
	v_and_b32_e32 v15, 0xffff0000, v15
	s_waitcnt vmcnt(0)
	v_lshlrev_b32_e32 v30, 16, v0
	v_and_b32_e32 v0, 0xffff0000, v0
	v_lshlrev_b32_e32 v31, 16, v1
	v_and_b32_e32 v1, 0xffff0000, v1
	v_cvt_pk_f16_f32 v166, v16, v2
	v_cvt_pk_f16_f32 v167, v17, v3
	v_cvt_pk_f16_f32 v168, v18, v4
	v_cvt_pk_f16_f32 v169, v19, v5
	v_cvt_pk_f16_f32 v170, v20, v6
	v_cvt_pk_f16_f32 v171, v21, v7
	v_cvt_pk_f16_f32 v172, v22, v8
	v_cvt_pk_f16_f32 v173, v23, v9
	v_cvt_pk_f16_f32 v174, v24, v10
	v_cvt_pk_f16_f32 v175, v25, v11
	v_cvt_pk_f16_f32 v177, v26, v12
	v_cvt_pk_f16_f32 v178, v27, v13
	v_cvt_pk_f16_f32 v179, v28, v14
	v_cvt_pk_f16_f32 v180, v29, v15
	v_cvt_pk_f16_f32 v181, v30, v0
	v_cvt_pk_f16_f32 v182, v31, v1
	ds_write2st64_b32 v142, v144, v145 offset0:18 offset1:20
	ds_write2st64_b32 v143, v146, v147 offset0:18 offset1:20
	s_branch .LBB0_1015

.LBB0_1015:
	ds_read_b128 v[0:3], v183
	ds_read_b128 v[4:7], v183 offset:16
	ds_read_b128 v[8:11], v183 offset:32
	ds_read_b128 v[12:15], v183 offset:48
	s_waitcnt lgkmcnt(3)
	v_mul_lo_u32 v0, v0, s51
	v_add_u32_e32 v16, v0, v128
	v_add_u32_e32 v0, v0, v136
	global_load_dwordx4 v[106:109], v16, s[40:41]
	global_load_dwordx2 v[110:111], v0, s[40:41]
	v_mul_lo_u32 v0, v1, s51
	v_add_u32_e32 v1, v0, v128
	v_add_u32_e32 v0, v0, v136
	global_load_dwordx4 v[100:103], v1, s[40:41]
	global_load_dwordx2 v[104:105], v0, s[40:41]
	v_mul_lo_u32 v0, v2, s51
	v_add_u32_e32 v1, v0, v128
	v_add_u32_e32 v0, v0, v136
	global_load_dwordx4 v[94:97], v1, s[40:41]
	global_load_dwordx2 v[98:99], v0, s[40:41]
	v_mul_lo_u32 v0, v3, s51
	v_add_u32_e32 v1, v0, v128
	v_add_u32_e32 v0, v0, v136
	global_load_dwordx4 v[88:91], v1, s[40:41]
	global_load_dwordx2 v[92:93], v0, s[40:41]
	s_waitcnt lgkmcnt(2)
	v_mul_lo_u32 v0, v4, s51
	v_add_u32_e32 v1, v0, v128
	v_add_u32_e32 v0, v0, v136
	global_load_dwordx4 v[82:85], v1, s[40:41]
	global_load_dwordx2 v[86:87], v0, s[40:41]
	v_mul_lo_u32 v0, v5, s51
	v_add_u32_e32 v1, v0, v128
	v_add_u32_e32 v0, v0, v136
	global_load_dwordx4 v[76:79], v1, s[40:41]
	global_load_dwordx2 v[80:81], v0, s[40:41]
	v_mul_lo_u32 v0, v6, s51
	v_add_u32_e32 v1, v0, v128
	v_add_u32_e32 v0, v0, v136
	global_load_dwordx4 v[70:73], v1, s[40:41]
	global_load_dwordx2 v[74:75], v0, s[40:41]
	v_mul_lo_u32 v0, v7, s51
	v_add_u32_e32 v1, v0, v128
	v_add_u32_e32 v0, v0, v136
	global_load_dwordx4 v[64:67], v1, s[40:41]
	global_load_dwordx2 v[68:69], v0, s[40:41]
	s_waitcnt lgkmcnt(1)
	v_mul_lo_u32 v0, v8, s51
	v_add_u32_e32 v1, v0, v128
	v_add_u32_e32 v0, v0, v136
	global_load_dwordx4 v[58:61], v1, s[40:41]
	global_load_dwordx2 v[62:63], v0, s[40:41]
	v_mul_lo_u32 v0, v9, s51
	v_add_u32_e32 v1, v0, v128
	v_add_u32_e32 v0, v0, v136
	global_load_dwordx4 v[52:55], v1, s[40:41]
	global_load_dwordx2 v[56:57], v0, s[40:41]
	v_mul_lo_u32 v0, v10, s51
	v_add_u32_e32 v1, v0, v128
	v_add_u32_e32 v0, v0, v136
	global_load_dwordx4 v[46:49], v1, s[40:41]
	global_load_dwordx2 v[50:51], v0, s[40:41]
	v_mul_lo_u32 v0, v11, s51
	v_add_u32_e32 v1, v0, v128
	v_add_u32_e32 v0, v0, v136
	global_load_dwordx4 v[40:43], v1, s[40:41]
	global_load_dwordx2 v[44:45], v0, s[40:41]
	s_waitcnt lgkmcnt(0)
	v_mul_lo_u32 v0, v12, s51
	v_add_u32_e32 v1, v0, v128
	v_add_u32_e32 v0, v0, v136
	global_load_dwordx4 v[34:37], v1, s[40:41]
	global_load_dwordx2 v[38:39], v0, s[40:41]
	v_mul_lo_u32 v0, v13, s51
	v_add_u32_e32 v1, v0, v128
	v_add_u32_e32 v0, v0, v136
	global_load_dwordx4 v[28:31], v1, s[40:41]
	global_load_dwordx2 v[32:33], v0, s[40:41]
	v_mul_lo_u32 v0, v14, s51
	v_add_u32_e32 v1, v0, v128
	v_add_u32_e32 v0, v0, v136
	global_load_dwordx4 v[22:25], v1, s[40:41]
	global_load_dwordx2 v[26:27], v0, s[40:41]
	v_mul_lo_u32 v0, v15, s51
	v_add_u32_e32 v1, v0, v128
	v_add_u32_e32 v0, v0, v136
	global_load_dwordx4 v[16:19], v1, s[40:41]
	global_load_dwordx2 v[20:21], v0, s[40:41]

.LBB0_1029:
	s_andn2_saveexec_b64 s[44:45], s[44:45]
	s_cbranch_execz .LBB0_1013
	v_mul_f32_e32 v3, v2, v2
	v_fmamk_f32 v4, v3, 0xba1345e1, v125
	v_fmaak_f32 v4, v3, v4, 0xbcdac9b8
	v_fmaak_f32 v4, v3, v4, 0x3de703be
	v_fmaak_f32 v4, v3, v4, 0xbec09330
	v_fmaak_f32 v3, v3, v4, 0x3e0375d0
	v_fma_f32 v3, |v2|, v3, |v2|
	s_branch .LBB0_1013
.LBB0_1038:
	s_or_b64 exec, exec, s[30:31]
	s_waitcnt vmcnt(0)
	s_barrier
	s_mov_b64 s[4:5], exec
	v_readlane_b32 s6, v250, 0
	v_readlane_b32 s7, v250, 1
	s_and_b64 s[6:7], s[4:5], s[6:7]
	s_mov_b64 exec, s[6:7]
	s_cbranch_execz .LBB0_1090
	v_mov_b32_e32 v0, 0x24008
	s_waitcnt vmcnt(0) expcnt(0) lgkmcnt(0)
	ds_read_b32 v2, v0
	v_mov_b32_e32 v0, 0x2400c
	ds_read_b32 v0, v0
	s_waitcnt lgkmcnt(1)
	v_cmp_ne_u32_e32 vcc, 0, v2
	s_cbranch_vccnz .LBB0_1054
	s_load_dword s6, s[0:1], 0x108
	s_mov_b32 s49, 1
	v_mov_b32_e32 v16, 0
	s_waitcnt lgkmcnt(0)
	s_mul_i32 s48, s71, s6
	s_add_u32 s6, s92, 0x1a3200
	s_addc_u32 s7, s93, 0
	s_add_u32 s8, s92, 0x1a3400
	s_addc_u32 s9, s93, 0
	s_add_u32 s10, s92, 0x1a3500
	s_addc_u32 s11, s93, 0
	s_add_u32 s12, s92, 0x1a3600
	s_addc_u32 s13, s93, 0
	s_add_u32 s14, s92, 0x1a3700
	s_addc_u32 s15, s93, 0
	s_add_u32 s16, s92, 0x1a3800
	s_addc_u32 s17, s93, 0
	s_add_u32 s18, s92, 0x1a3900
	s_addc_u32 s19, s93, 0
	s_add_u32 s20, s92, 0x1a3a00
	s_addc_u32 s21, s93, 0
	s_add_u32 s22, s92, 0x1a3b00
	s_addc_u32 s23, s93, 0
	s_add_u32 s24, s92, 0x1a3c00
	s_addc_u32 s25, s93, 0
	s_add_u32 s26, s92, 0x1a3d00
	s_addc_u32 s27, s93, 0
	s_add_u32 s28, s92, 0x1a3e00
	s_addc_u32 s29, s93, 0
	s_add_u32 s30, s92, 0x1a3f00
	s_addc_u32 s31, s93, 0
	s_add_u32 s34, s92, 0x1a4000
	s_addc_u32 s35, s93, 0
	s_add_u32 s36, s92, 0x1a4100
	s_addc_u32 s37, s93, 0
	s_add_u32 s38, s92, 0x1a4200
	s_addc_u32 s39, s93, 0
	s_add_u32 s40, s92, 0x1a4300
	s_mul_i32 s48, s48, s70
	s_addc_u32 s41, s93, 0
	s_branch .LBB0_1042
